# GLA chunk epilogue pair_tiles via v_permlane16_swap only (no read batching); on top of v44
# baseline (speedup 1.0000x reference)
; #define LAS __attribute__((address_space(3)))
; #define LDS_BARRIER() asm volatile("s_waitcnt lgkmcnt(0)\n\ts_barrier" ::: "memory")
; __device__ __forceinline__ void gla_phase(LAS unsigned char* lds, const bf16_t* P, const float* hn, bf16_t* O, int G, int wg) {
;     ...
;             for (int i = 0; i < 8; ++i) { q0[i] = bf2f(rq[i]); q1[i] = bf2f(rq[i] >> 16); l0[i] = bf2f(rl[i]) * LOG2E; l1[i] = bf2f(rl[i] >> 16) * LOG2E; run0 += l0[i]; b0[i] = run0; run1 += l1[i]; b1[i] = run1; }
; #pragma unroll
;             for (int i = 0; i < 4; ++i) { vt0[i] = (rv[2 * i] & 0xffffu) | (rv[2 * i + 1] << 16); vt1[i] = (rv[2 * i] >> 16) | (rv[2 * i + 1] & 0xffff0000u); }
;             { const int cn = (c < 31) ? c + 1 : 31;
;               const bf16_t* pp = pbase + (size_t)(cn * 64 + tq * 8) * 4096;
; #pragma unroll
;                 for (int i = 0; i < 8; ++i) { rq[i] = *(const unsigned*)(pp + (size_t)i * 4096); rl[i] = *(const unsigned*)(pp + (size_t)i * 4096 + 1024); rv[i] = *(const unsigned*)(pp + (size_t)i * 4096 + 2048); } }
;             *(LAS f32x2*)(lds + PART + (tq * 128 + 2 * dp) * 4) = (f32x2){run0, run1};
;             LDS_BARRIER();
;             if (c > 0) GLA_EPILOGUE(c - 1);
.LBB0_1402:
	s_add_i32 s94, s95, 64
	s_cmpk_eq_i32 s95, 0x7c0
	s_cselect_b32 s16, s95, s94
	v_add_u32_e32 v16, s16, v82
	v_ashrrev_i32_e32 v17, 31, v16
	v_lshlrev_b64 v[16:17], 13, v[16:17]
	v_lshl_add_u64 v[16:17], v[102:103], 0, v[16:17]
	v_add_co_u32_e32 v18, vcc, s23, v16
	s_waitcnt vmcnt(20)
	v_lshlrev_b32_e32 v40, 16, v93
	v_addc_co_u32_e32 v19, vcc, 0, v17, vcc
	v_add_co_u32_e32 v20, vcc, s31, v16
	v_and_b32_e32 v41, 0xffff0000, v93
	s_nop 0
	v_addc_co_u32_e32 v21, vcc, 0, v17, vcc
	v_add_co_u32_e32 v22, vcc, s33, v16
	s_waitcnt vmcnt(17)
	v_lshlrev_b32_e32 v42, 16, v97
	v_addc_co_u32_e32 v23, vcc, 0, v17, vcc
	v_add_co_u32_e32 v24, vcc, s19, v16
	v_and_b32_e32 v43, 0xffff0000, v97
	s_nop 0
	v_addc_co_u32_e32 v25, vcc, 0, v17, vcc
	v_add_co_u32_e32 v26, vcc, s92, v16
	s_waitcnt vmcnt(14)
	v_lshlrev_b32_e32 v44, 16, v185
	v_addc_co_u32_e32 v27, vcc, 0, v17, vcc
	v_and_b32_e32 v45, 0xffff0000, v185
	global_load_dword v191, v[22:23], off
	global_load_dword v93, v[22:23], off offset:2048
	global_load_dword v194, v[24:25], off offset:-4096
	global_load_dword v192, v[24:25], off
	global_load_dword v97, v[24:25], off offset:2048
	global_load_dword v195, v[26:27], off offset:-4096
	global_load_dword v193, v[26:27], off
	global_load_dword v185, v[26:27], off offset:2048
	v_add_co_u32_e32 v24, vcc, 0xb000, v16
	s_waitcnt vmcnt(14)
	v_lshlrev_b32_e32 v34, 16, v189
	v_addc_co_u32_e32 v25, vcc, 0, v17, vcc
	v_add_co_u32_e32 v26, vcc, s12, v16
	v_and_b32_e32 v35, 0xffff0000, v189
	s_nop 0
	v_addc_co_u32_e32 v27, vcc, 0, v17, vcc
	v_add_co_u32_e32 v28, vcc, 0xd000, v16
	v_lshlrev_b32_e32 v46, 16, v187
	s_nop 0
	v_addc_co_u32_e32 v29, vcc, 0, v17, vcc
	v_add_co_u32_e32 v30, vcc, 0xe000, v16
	v_and_b32_e32 v47, 0xffff0000, v187
	s_nop 0
	v_addc_co_u32_e32 v31, vcc, 0, v17, vcc
	v_lshlrev_b32_e32 v48, 16, v188
	v_and_b32_e32 v49, 0xffff0000, v188
	global_load_dword v197, v[16:17], off
	global_load_dword v189, v[16:17], off offset:2048
	global_load_dword v199, v[24:25], off
	global_load_dword v196, v[26:27], off
	global_load_dword v187, v[26:27], off offset:2048
	global_load_dword v201, v[28:29], off
	global_load_dword v198, v[30:31], off
	global_load_dword v188, v[30:31], off offset:2048
	v_add_co_u32_e32 v16, vcc, 0xf000, v16
	s_waitcnt vmcnt(19)
	v_lshlrev_b32_e32 v36, 16, v190
	v_and_b32_e32 v37, 0xffff0000, v190
	v_lshlrev_b32_e32 v38, 16, v186
	v_and_b32_e32 v39, 0xffff0000, v186
	v_addc_co_u32_e32 v17, vcc, 0, v17, vcc
	global_load_dword v203, v[18:19], off offset:-4096
	global_load_dword v200, v[18:19], off
	global_load_dword v190, v[18:19], off offset:2048
	global_load_dword v204, v[20:21], off offset:-4096
	global_load_dword v202, v[20:21], off
	global_load_dword v186, v[20:21], off offset:2048
	global_load_dword v206, v[22:23], off offset:-4096
	global_load_dword v205, v[16:17], off
	v_pk_fma_f32 v[30:31], v[34:35], s[18:19], 0 op_sel_hi:[1,0,0]
	s_cmp_eq_u32 s95, 0
	v_pk_fma_f32 v[28:29], v[36:37], s[18:19], v[30:31] op_sel_hi:[1,0,1]
	s_mov_b32 s16, 0
	v_pk_fma_f32 v[26:27], v[38:39], s[18:19], v[28:29] op_sel_hi:[1,0,1]
	s_nop 0
	v_pk_fma_f32 v[24:25], v[40:41], s[18:19], v[26:27] op_sel_hi:[1,0,1]
	s_nop 0
	v_pk_fma_f32 v[22:23], v[42:43], s[18:19], v[24:25] op_sel_hi:[1,0,1]
	s_nop 0
	v_pk_fma_f32 v[20:21], v[44:45], s[18:19], v[22:23] op_sel_hi:[1,0,1]
	s_nop 0
	v_pk_fma_f32 v[18:19], v[46:47], s[18:19], v[20:21] op_sel_hi:[1,0,1]
	s_nop 0
	v_pk_fma_f32 v[16:17], v[48:49], s[18:19], v[18:19] op_sel_hi:[1,0,1]
	s_waitcnt lgkmcnt(0)
	s_barrier
	ds_write_b64 v161, v[16:17]
	s_waitcnt lgkmcnt(0)
	s_barrier
	s_cbranch_scc1 .LBB0_1404
	ds_read2st64_b32 v[50:51], v146 offset1:1
	s_sub_i32 s16, s95, 64
	s_waitcnt lgkmcnt(0)
	v_add_f32_e32 v32, v50, v51
	v_add_u32_e32 v50, 0, v147
	v_fmamk_f32 v32, v32, 0x3c000000, v211
	v_add_u32_e32 v56, 0x1b200, v50
	v_rsq_f32_e32 v32, v32
	ds_read_b128 v[50:53], v56
	v_pk_mul_f32 v[12:13], v[12:13], v[32:33] op_sel_hi:[1,0]
	v_pk_mul_f32 v[8:9], v[8:9], v[32:33] op_sel_hi:[1,0]
	s_waitcnt lgkmcnt(0)
	v_pk_mul_f32 v[12:13], v[50:51], v[12:13]
	v_lshlrev_b32_e32 v50, 16, v142
	v_and_b32_e32 v51, 0xffff0000, v142
	v_pk_mul_f32 v[12:13], v[12:13], v[50:51]
	v_pk_mul_f32 v[4:5], v[4:5], v[32:33] op_sel_hi:[1,0]
	v_cvt_pk_bf16_f32 v50, v12, v13
	v_pk_mul_f32 v[12:13], v[14:15], v[32:33] op_sel_hi:[1,0]
	v_lshlrev_b32_e32 v14, 16, v143
	v_pk_mul_f32 v[12:13], v[52:53], v[12:13]
	v_and_b32_e32 v15, 0xffff0000, v143
	v_pk_mul_f32 v[12:13], v[12:13], v[14:15]
	v_pk_mul_f32 v[0:1], v[0:1], v[32:33] op_sel_hi:[1,0]
	v_cvt_pk_bf16_f32 v51, v12, v13
	ds_read_b128 v[12:15], v56 offset:64
	s_waitcnt lgkmcnt(0)
	v_pk_mul_f32 v[8:9], v[12:13], v[8:9]
	s_waitcnt vmcnt(26)
	v_lshlrev_b32_e32 v12, 16, v140
	v_and_b32_e32 v13, 0xffff0000, v140
	v_pk_mul_f32 v[8:9], v[8:9], v[12:13]
	s_nop 0
	v_cvt_pk_bf16_f32 v12, v8, v9
	v_pk_mul_f32 v[8:9], v[10:11], v[32:33] op_sel_hi:[1,0]
	v_lshlrev_b32_e32 v10, 16, v141
	v_pk_mul_f32 v[8:9], v[14:15], v[8:9]
	v_and_b32_e32 v11, 0xffff0000, v141
	v_pk_mul_f32 v[8:9], v[8:9], v[10:11]
	s_nop 0
	v_cvt_pk_bf16_f32 v13, v8, v9
	ds_read_b128 v[8:11], v56 offset:128
	s_waitcnt lgkmcnt(0)
	v_pk_mul_f32 v[4:5], v[8:9], v[4:5]
	s_waitcnt vmcnt(25)
	v_lshlrev_b32_e32 v8, 16, v114
	v_and_b32_e32 v9, 0xffff0000, v114
	v_pk_mul_f32 v[4:5], v[4:5], v[8:9]
	s_nop 0
	v_cvt_pk_bf16_f32 v8, v4, v5
	v_pk_mul_f32 v[4:5], v[6:7], v[32:33] op_sel_hi:[1,0]
	v_lshlrev_b32_e32 v6, 16, v115
	v_pk_mul_f32 v[4:5], v[10:11], v[4:5]
	v_and_b32_e32 v7, 0xffff0000, v115
	v_pk_mul_f32 v[4:5], v[4:5], v[6:7]
	s_nop 0
	v_cvt_pk_bf16_f32 v9, v4, v5
	ds_read_b128 v[4:7], v56 offset:192
	s_waitcnt lgkmcnt(0)
	v_pk_mul_f32 v[0:1], v[0:1], v[4:5]
	s_waitcnt vmcnt(24)
	v_lshlrev_b32_e32 v4, 16, v100
	v_and_b32_e32 v5, 0xffff0000, v100
	v_pk_mul_f32 v[0:1], v[0:1], v[4:5]
	s_nop 0
	v_cvt_pk_bf16_f32 v10, v0, v1
	v_pk_mul_f32 v[0:1], v[2:3], v[32:33] op_sel_hi:[1,0]
	v_lshlrev_b32_e32 v2, 16, v101
	v_pk_mul_f32 v[0:1], v[0:1], v[6:7]
	v_and_b32_e32 v3, 0xffff0000, v101
	v_pk_mul_f32 v[0:1], v[0:1], v[2:3]
	s_nop 0
	v_cvt_pk_bf16_f32 v11, v0, v1
	v_lshl_add_u64 v[0:1], v[98:99], 0, s[16:17]
	v_lshlrev_b64 v[4:5], 11, v[0:1]
	v_lshl_add_u64 v[4:5], v[104:105], 0, v[4:5]
	s_mov_b32 s16, s95
	v_permlane16_swap_b32_e32 v50, v12
	v_permlane16_swap_b32_e32 v51, v13
	v_permlane16_swap_b32_e32 v8, v10
	v_permlane16_swap_b32_e32 v9, v11
	global_store_dwordx2 v[4:5], v[50:51], off
	global_store_dwordx2 v[4:5], v[12:13], off offset:8
	global_store_dwordx4 v[4:5], v[8:11], off offset:64
